# v25 + L2 warming of the next GEMM phase's first B K-tiles by the non-barrier waves before group barriers 5, 6, 7
# baseline (speedup 1.0000x reference)
; __device__ __forceinline__ unsigned xb_add(unsigned* p, unsigned v) { return __hip_atomic_fetch_add(p, v, __ATOMIC_RELAXED, __HIP_MEMORY_SCOPE_AGENT); }
; __device__ __forceinline__ void xcd_barrier(const XcdBarrier& b) {
;     asm volatile("s_waitcnt vmcnt(0)" ::: "memory");
;     __syncthreads();
;     if (threadIdx.x == 0) {
;         unsigned* bar = b.bar;
;         __builtin_amdgcn_s_waitcnt(0);
;         unsigned nloc = b.st[0], nx = b.st[1];
;         if (nloc == 0u) { xcd_barrier_complete(bar, b.x, nloc, nx); b.st[0] = nloc; b.st[1] = nx; }
;         const unsigned old = xb_add(&bar[XB_XSUB(b.x)], 1u);
.LBB0_1103:
	s_waitcnt vmcnt(0)
	s_barrier
	v_readfirstlane_b32 s100, v0
	s_cmp_eq_u32 s100, 0
	s_cbranch_scc1 .Lwarm5
	s_and_b32 s100, s98, -4
	s_sub_u32 s100, s100, s99
	s_lshr_b32 s100, s100, 3
	s_and_b32 s100, s100, 3
	s_lshl_b32 s100, s100, 19
	s_add_u32 s100, s100, 0xe00000
	s_add_u32 s100, s88, s100
	s_addc_u32 s101, s89, 0
	v_subrev_u32_e32 v1, 64, v0
	v_lshrrev_b32_e32 v2, 1, v1
	v_and_b32_e32 v3, 1, v1
	v_lshlrev_b32_e32 v2, 11, v2
	v_lshl_or_b32 v2, v3, 7, v2
	global_load_dword v242, v2, s[100:101]
	v_add_u32_e32 v1, 0x1c0, v1
	v_and_b32_e32 v1, 0x1ff, v1
	v_lshrrev_b32_e32 v2, 1, v1
	v_and_b32_e32 v3, 1, v1
	v_lshlrev_b32_e32 v2, 11, v2
	v_lshl_or_b32 v2, v3, 7, v2
	global_load_dword v242, v2, s[100:101]
.Lwarm5:
	s_mov_b64 s[2:3], exec
	v_readlane_b32 s4, v241, 34
	v_readlane_b32 s5, v241, 35
	s_and_b64 s[4:5], s[2:3], s[4:5]
	s_mov_b64 exec, s[4:5]
	s_cbranch_execz .LBB0_1155
	s_bitcmp1_b32 s98, 0
	s_cbranch_scc1 .Lgb_orig5
	s_waitcnt vmcnt(0) lgkmcnt(0)
	s_and_b32 s100, s98, -4
	s_addk_i32 s100, 0x1000
	v_mov_b32_e32 v1, s100
	v_mov_b32_e32 v2, 1
	global_store_dword v1, v2, s[88:89] offset:1024
	buffer_inv sc1
	s_mov_b32 exec_lo, -1
	s_mov_b32 exec_hi, 0
	v_mbcnt_lo_u32_b32 v3, -1, 0
	v_lshl_add_u32 v3, v3, 2, s99
	v_add_u32_e32 v3, 0x1000, v3
	s_mov_b32 s100, 0

; __device__ __forceinline__ unsigned xb_add(unsigned* p, unsigned v) { return __hip_atomic_fetch_add(p, v, __ATOMIC_RELAXED, __HIP_MEMORY_SCOPE_AGENT); }
; __device__ __forceinline__ void xcd_barrier(const XcdBarrier& b) {
;     asm volatile("s_waitcnt vmcnt(0)" ::: "memory");
;     __syncthreads();
;     if (threadIdx.x == 0) {
;         unsigned* bar = b.bar;
;         __builtin_amdgcn_s_waitcnt(0);
;         unsigned nloc = b.st[0], nx = b.st[1];
;         if (nloc == 0u) { xcd_barrier_complete(bar, b.x, nloc, nx); b.st[0] = nloc; b.st[1] = nx; }
;         const unsigned old = xb_add(&bar[XB_XSUB(b.x)], 1u);
.LBB0_1242:
	s_waitcnt vmcnt(0)
	s_waitcnt lgkmcnt(0)
	s_barrier
	v_readfirstlane_b32 s100, v0
	s_cmp_eq_u32 s100, 0
	s_cbranch_scc1 .Lwarm6
	s_and_b32 s100, s98, -4
	s_sub_u32 s100, s100, s99
	s_lshr_b32 s100, s100, 4
	s_and_b32 s100, s100, 7
	s_lshl_b32 s100, s100, 19
	s_add_u32 s100, s100, 0x1000000
	s_add_u32 s100, s88, s100
	s_addc_u32 s101, s89, 0
	v_subrev_u32_e32 v1, 64, v0
	v_lshrrev_b32_e32 v2, 1, v1
	v_and_b32_e32 v3, 1, v1
	v_lshlrev_b32_e32 v2, 11, v2
	v_lshl_or_b32 v2, v3, 7, v2
	global_load_dword v242, v2, s[100:101]
	v_add_u32_e32 v1, 0x1c0, v1
	v_and_b32_e32 v1, 0x1ff, v1
	v_lshrrev_b32_e32 v2, 1, v1
	v_and_b32_e32 v3, 1, v1
	v_lshlrev_b32_e32 v2, 11, v2
	v_lshl_or_b32 v2, v3, 7, v2
	global_load_dword v242, v2, s[100:101]
.Lwarm6:
	s_mov_b64 s[0:1], exec
	v_readlane_b32 s6, v241, 34
	v_readlane_b32 s7, v241, 35
	v_readlane_b32 s78, v241, 55
	s_and_b64 s[6:7], s[0:1], s[6:7]
	v_readlane_b32 s79, v241, 56
	s_mov_b64 exec, s[6:7]
	s_cbranch_execz .LBB0_1294
	s_bitcmp1_b32 s98, 0
	s_cbranch_scc1 .Lgb_orig6
	s_waitcnt vmcnt(0) lgkmcnt(0)
	s_and_b32 s100, s98, -4
	s_addk_i32 s100, 0x1000
	v_mov_b32_e32 v1, s100
	v_mov_b32_e32 v2, 1
	global_store_dword v1, v2, s[88:89] offset:2048
	buffer_inv sc1
	s_mov_b32 exec_lo, -1
	s_mov_b32 exec_hi, 0
	v_mbcnt_lo_u32_b32 v3, -1, 0
	v_lshl_add_u32 v3, v3, 2, s99
	v_add_u32_e32 v3, 0x1000, v3
	s_mov_b32 s100, 0

; __device__ __forceinline__ unsigned xb_add(unsigned* p, unsigned v) { return __hip_atomic_fetch_add(p, v, __ATOMIC_RELAXED, __HIP_MEMORY_SCOPE_AGENT); }
; __device__ __forceinline__ void xcd_barrier(const XcdBarrier& b) {
;     asm volatile("s_waitcnt vmcnt(0)" ::: "memory");
;     __syncthreads();
;     if (threadIdx.x == 0) {
;         unsigned* bar = b.bar;
;         __builtin_amdgcn_s_waitcnt(0);
;         unsigned nloc = b.st[0], nx = b.st[1];
;         if (nloc == 0u) { xcd_barrier_complete(bar, b.x, nloc, nx); b.st[0] = nloc; b.st[1] = nx; }
;         const unsigned old = xb_add(&bar[XB_XSUB(b.x)], 1u);
.LBB0_1352:
	s_waitcnt vmcnt(0)
	s_waitcnt vmcnt(0)
	s_barrier
	v_readfirstlane_b32 s100, v0
	s_cmp_eq_u32 s100, 0
	s_cbranch_scc1 .Lwarm7
	s_and_b32 s100, s98, -4
	s_sub_u32 s100, s100, s99
	s_lshr_b32 s100, s100, 3
	s_and_b32 s100, s100, 3
	s_lshl_b32 s100, s100, 21
	s_add_u32 s100, s100, 0x1800000
	s_add_u32 s100, s88, s100
	s_addc_u32 s101, s89, 0
	v_subrev_u32_e32 v1, 64, v0
	v_lshrrev_b32_e32 v2, 1, v1
	v_and_b32_e32 v3, 1, v1
	v_lshlrev_b32_e32 v2, 13, v2
	v_lshl_or_b32 v2, v3, 7, v2
	global_load_dword v242, v2, s[100:101]
	v_add_u32_e32 v1, 0x1c0, v1
	v_and_b32_e32 v1, 0x1ff, v1
	v_lshrrev_b32_e32 v2, 1, v1
	v_and_b32_e32 v3, 1, v1
	v_lshlrev_b32_e32 v2, 13, v2
	v_lshl_or_b32 v2, v3, 7, v2
	global_load_dword v242, v2, s[100:101]
.Lwarm7:
	s_mov_b64 s[0:1], exec
	v_readlane_b32 s6, v241, 34
	v_readlane_b32 s7, v241, 35
	s_and_b64 s[6:7], s[0:1], s[6:7]
	s_mov_b64 exec, s[6:7]
	s_cbranch_execz .LBB0_1404
	s_bitcmp1_b32 s98, 0
	s_cbranch_scc1 .Lgb_orig7
	s_waitcnt vmcnt(0) lgkmcnt(0)
	s_and_b32 s100, s98, -4
	s_addk_i32 s100, 0x1000
	v_mov_b32_e32 v1, s100
	v_mov_b32_e32 v2, 1
	global_store_dword v1, v2, s[88:89] offset:3072
	buffer_inv sc1
	s_mov_b32 exec_lo, -1
	s_mov_b32 exec_hi, 0
	v_mbcnt_lo_u32_b32 v3, -1, 0
	v_lshl_add_u32 v3, v3, 2, s99
	v_add_u32_e32 v3, 0x1000, v3
	s_mov_b32 s100, 0

; __global__ void __launch_bounds__(NWAVES * 64, 2) skel_fwd(Args args) {
;     extern __shared__ __attribute__((aligned(16))) unsigned char lds[];
	.amdhsa_kernel _Z8skel_fwd4Args
		.amdhsa_group_segment_fixed_size 0
		.amdhsa_private_segment_fixed_size 0
		.amdhsa_kernarg_size 456
		.amdhsa_user_sgpr_count 2
		.amdhsa_user_sgpr_dispatch_ptr 0
		.amdhsa_user_sgpr_queue_ptr 0
		.amdhsa_user_sgpr_kernarg_segment_ptr 1
		.amdhsa_user_sgpr_dispatch_id 0
		.amdhsa_user_sgpr_kernarg_preload_length 0
		.amdhsa_user_sgpr_kernarg_preload_offset 0
		.amdhsa_user_sgpr_private_segment_size 0
		.amdhsa_uses_dynamic_stack 0
		.amdhsa_enable_private_segment 0
		.amdhsa_system_sgpr_workgroup_id_x 1
		.amdhsa_system_sgpr_workgroup_id_y 0
		.amdhsa_system_sgpr_workgroup_id_z 0
		.amdhsa_system_sgpr_workgroup_info 0
		.amdhsa_system_vgpr_workitem_id 0
		.amdhsa_next_free_vgpr 243
		.amdhsa_next_free_sgpr 102
		.amdhsa_accum_offset 244
		.amdhsa_reserve_vcc 1
		.amdhsa_float_round_mode_32 0
		.amdhsa_float_round_mode_16_64 0
		.amdhsa_float_denorm_mode_32 3
		.amdhsa_float_denorm_mode_16_64 3
		.amdhsa_dx10_clamp 1
		.amdhsa_ieee_mode 1
		.amdhsa_fp16_overflow 0
		.amdhsa_tg_split 0
		.amdhsa_exception_fp_ieee_invalid_op 0
		.amdhsa_exception_fp_denorm_src 0
		.amdhsa_exception_fp_ieee_div_zero 0
		.amdhsa_exception_fp_ieee_overflow 0
		.amdhsa_exception_fp_ieee_underflow 0
		.amdhsa_exception_fp_ieee_inexact 0
		.amdhsa_exception_int_div_zero 0
	.end_amdhsa_kernel

; __global__ void __launch_bounds__(NWAVES * 64, 2) skel_fwd(Args args) {
;     extern __shared__ __attribute__((aligned(16))) unsigned char lds[];
amdhsa.kernels:
  - .agpr_count:     0
    .args:
      - .offset:         0
        .size:           200
        .value_kind:     by_value
      - .offset:         200
        .size:           4
        .value_kind:     hidden_block_count_x
      - .offset:         204
        .size:           4
        .value_kind:     hidden_block_count_y
      - .offset:         208
        .size:           4
        .value_kind:     hidden_block_count_z
      - .offset:         212
        .size:           2
        .value_kind:     hidden_group_size_x
      - .offset:         214
        .size:           2
        .value_kind:     hidden_group_size_y
      - .offset:         216
        .size:           2
        .value_kind:     hidden_group_size_z
      - .offset:         218
        .size:           2
        .value_kind:     hidden_remainder_x
      - .offset:         220
        .size:           2
        .value_kind:     hidden_remainder_y
      - .offset:         222
        .size:           2
        .value_kind:     hidden_remainder_z
      - .offset:         240
        .size:           8
        .value_kind:     hidden_global_offset_x
      - .offset:         248
        .size:           8
        .value_kind:     hidden_global_offset_y
      - .offset:         256
        .size:           8
        .value_kind:     hidden_global_offset_z
      - .offset:         264
        .size:           2
        .value_kind:     hidden_grid_dims
      - .offset:         320
        .size:           4
        .value_kind:     hidden_dynamic_lds_size
    .group_segment_fixed_size: 0
    .kernarg_segment_align: 8
    .kernarg_segment_size: 456
    .language:       OpenCL C
    .language_version:
      - 2
      - 0
    .max_flat_workgroup_size: 512
    .name:           _Z8skel_fwd4Args
    .private_segment_fixed_size: 0
    .sgpr_count:     108
    .sgpr_spill_count: 85
    .symbol:         _Z8skel_fwd4Args.kd
    .uniform_work_group_size: 1
    .uses_dynamic_stack: false
    .vgpr_count:     243
    .vgpr_spill_count: 0
    .wavefront_size: 64
